# attention: next round Q fragments prefetched during the context-PV block (into idle V-ring fragment registers), on top of v34
# baseline (speedup 1.0000x reference)
; #define LAS __attribute__((address_space(3)))
; template <bool LOCAL>
; __device__ __forceinline__ void attn_unit(const bf16_t* Q, const bf16_t* KT, const bf16_t* VT, bf16_t* O, LAS unsigned char* lds, int b, int h, int r, int w, int tq, int lane) {
;     ...
;     { const bf16_t* qp = Q + (size_t)qrow * D + h * HD + 8 * g;
; #pragma unroll
;       for (int ks = 0; ks < 4; ++ks) bq[ks] = *(const bf16x8*)(qp + 32 * ks); }
;     ...
;     {
;         const LAS unsigned char* vl = lds + 65536 + g * 2048 + q * 16;
; #pragma unroll
;         for (int p = 0; p < 8; ++p)
; #pragma unroll
;             for (int df = 0; df < 8; ++df) o[df] = __builtin_amdgcn_mfma_f32_16x16x32_bf16(*(const LAS bf16x8*)(vl + p * 8192 + df * 256), pb[CP + p], o[df], 0, 0, 0);
;     }
.Lrg_v_B_end:
.Lrg_v_done:
	s_barrier
	v_mov_b32_e32 v222, v234
	v_mov_b32_e32 v223, v235
	s_lshl_b32 s55, s57, 10
	s_add_i32 m0, s55, 0
	s_nop 0
	global_load_lds_dwordx4 v[222:223], off
	v_add_co_u32_e32 v222, vcc, 0x20000, v222
	s_nop 1
	v_addc_co_u32_e32 v223, vcc, 0, v223, vcc
	s_add_i32 m0, s55, 8192
	s_nop 0
	global_load_lds_dwordx4 v[222:223], off
	v_add_co_u32_e32 v222, vcc, 0x20000, v222
	s_nop 1
	v_addc_co_u32_e32 v223, vcc, 0, v223, vcc
	s_add_i32 m0, s55, 16384
	s_nop 0
	global_load_lds_dwordx4 v[222:223], off
	v_add_co_u32_e32 v222, vcc, 0x20000, v222
	s_nop 1
	v_addc_co_u32_e32 v223, vcc, 0, v223, vcc
	s_add_i32 m0, s55, 24576
	s_nop 0
	global_load_lds_dwordx4 v[222:223], off
	v_add_co_u32_e32 v222, vcc, 0x20000, v222
	s_nop 1
	v_addc_co_u32_e32 v223, vcc, 0, v223, vcc
	s_add_i32 m0, s55, 32768
	s_nop 0
	global_load_lds_dwordx4 v[222:223], off
	v_add_co_u32_e32 v222, vcc, 0x20000, v222
	s_nop 1
	v_addc_co_u32_e32 v223, vcc, 0, v223, vcc
	s_add_i32 m0, s55, 40960
	s_nop 0
	global_load_lds_dwordx4 v[222:223], off
	v_add_co_u32_e32 v222, vcc, 0x20000, v222
	s_nop 1
	v_addc_co_u32_e32 v223, vcc, 0, v223, vcc
	s_add_i32 m0, s55, 49152
	s_nop 0
	global_load_lds_dwordx4 v[222:223], off
	v_add_co_u32_e32 v222, vcc, 0x20000, v222
	s_nop 1
	v_addc_co_u32_e32 v223, vcc, 0, v223, vcc
	s_add_i32 m0, s55, 57344
	s_nop 0
	global_load_lds_dwordx4 v[222:223], off
	s_waitcnt lgkmcnt(0)
	s_add_i32 s48, s48, 2
	s_add_i32 s52, s52, s80
	s_sub_i32 s51, s51, s80
	s_lshl_b32 s82, s80, 6
	v_add_u32_e32 v162, s82, v162
	s_cmp_eq_u32 s48, 8
	s_cbranch_scc1 .Lqpf_skip
	v_ashrrev_i32_e32 v163, 31, v162
	v_lshlrev_b64 v[58:59], 12, v[162:163]
	v_lshl_add_u64 v[58:59], v[158:159], 0, v[58:59]
	global_load_dwordx4 v[106:109], v[58:59], off
	global_load_dwordx4 v[110:113], v[58:59], off offset:64
	global_load_dwordx4 v[114:117], v[58:59], off offset:128
	global_load_dwordx4 v[118:121], v[58:59], off offset:192
.Lqpf_skip:
	ds_read_b128 v[200:203], v178
	ds_read_b128 v[204:207], v178 offset:256
	ds_read_b128 v[208:211], v178 offset:512
	ds_read_b128 v[212:215], v178 offset:768
	ds_read_b128 v[216:219], v178 offset:1024
	ds_read_b128 v[220:223], v178 offset:1280
	ds_read_b128 v[224:227], v178 offset:1536
	ds_read_b128 v[228:231], v178 offset:1792
	s_waitcnt lgkmcnt(7)
	v_mfma_f32_16x16x32_bf16 v[22:25], v[200:203], v[98:101], v[22:25]
	ds_read_b128 v[200:203], v178 offset:8192
	s_waitcnt lgkmcnt(7)
	v_mfma_f32_16x16x32_bf16 v[30:33], v[204:207], v[98:101], v[30:33]
	ds_read_b128 v[204:207], v178 offset:8448
	s_waitcnt lgkmcnt(7)
	v_mfma_f32_16x16x32_bf16 v[34:37], v[208:211], v[98:101], v[34:37]
	ds_read_b128 v[208:211], v178 offset:8704
	s_waitcnt lgkmcnt(7)
	v_mfma_f32_16x16x32_bf16 v[38:41], v[212:215], v[98:101], v[38:41]
	ds_read_b128 v[212:215], v178 offset:8960
	s_waitcnt lgkmcnt(7)
	v_mfma_f32_16x16x32_bf16 v[42:45], v[216:219], v[98:101], v[42:45]
	ds_read_b128 v[216:219], v178 offset:9216
	s_waitcnt lgkmcnt(7)
	v_mfma_f32_16x16x32_bf16 v[46:49], v[220:223], v[98:101], v[46:49]
	ds_read_b128 v[220:223], v178 offset:9472
	s_waitcnt lgkmcnt(7)
	v_mfma_f32_16x16x32_bf16 v[50:53], v[224:227], v[98:101], v[50:53]
	ds_read_b128 v[224:227], v178 offset:9728
	s_waitcnt lgkmcnt(7)
	v_mfma_f32_16x16x32_bf16 v[54:57], v[228:231], v[98:101], v[54:57]
	ds_read_b128 v[228:231], v178 offset:9984
	s_waitcnt lgkmcnt(7)
	v_mfma_f32_16x16x32_bf16 v[22:25], v[200:203], v[90:93], v[22:25]
	ds_read_b128 v[200:203], v178 offset:16384
	s_waitcnt lgkmcnt(7)
	v_mfma_f32_16x16x32_bf16 v[30:33], v[204:207], v[90:93], v[30:33]
	ds_read_b128 v[204:207], v178 offset:16640
	s_waitcnt lgkmcnt(7)
	v_mfma_f32_16x16x32_bf16 v[34:37], v[208:211], v[90:93], v[34:37]
	ds_read_b128 v[208:211], v178 offset:16896
	s_waitcnt lgkmcnt(7)
	v_mfma_f32_16x16x32_bf16 v[38:41], v[212:215], v[90:93], v[38:41]
	ds_read_b128 v[212:215], v178 offset:17152
	s_waitcnt lgkmcnt(7)
	v_mfma_f32_16x16x32_bf16 v[42:45], v[216:219], v[90:93], v[42:45]
	ds_read_b128 v[216:219], v178 offset:17408
	s_waitcnt lgkmcnt(7)
	v_mfma_f32_16x16x32_bf16 v[46:49], v[220:223], v[90:93], v[46:49]
	ds_read_b128 v[220:223], v178 offset:17664
	s_waitcnt lgkmcnt(7)
	v_mfma_f32_16x16x32_bf16 v[50:53], v[224:227], v[90:93], v[50:53]
	ds_read_b128 v[224:227], v178 offset:17920
	s_waitcnt lgkmcnt(7)
	v_mfma_f32_16x16x32_bf16 v[54:57], v[228:231], v[90:93], v[54:57]
	ds_read_b128 v[228:231], v178 offset:18176
	s_waitcnt lgkmcnt(7)
	v_mfma_f32_16x16x32_bf16 v[22:25], v[200:203], v[26:29], v[22:25]
	ds_read_b128 v[200:203], v178 offset:24576
	s_waitcnt lgkmcnt(7)
	v_mfma_f32_16x16x32_bf16 v[30:33], v[204:207], v[26:29], v[30:33]
	ds_read_b128 v[204:207], v178 offset:24832
	s_waitcnt lgkmcnt(7)
	v_mfma_f32_16x16x32_bf16 v[34:37], v[208:211], v[26:29], v[34:37]
	ds_read_b128 v[208:211], v178 offset:25088
	s_waitcnt lgkmcnt(7)
	v_mfma_f32_16x16x32_bf16 v[38:41], v[212:215], v[26:29], v[38:41]
	ds_read_b128 v[212:215], v178 offset:25344
	s_waitcnt lgkmcnt(7)
	v_mfma_f32_16x16x32_bf16 v[42:45], v[216:219], v[26:29], v[42:45]
	ds_read_b128 v[216:219], v178 offset:25600
	s_waitcnt lgkmcnt(7)
	v_mfma_f32_16x16x32_bf16 v[46:49], v[220:223], v[26:29], v[46:49]
	ds_read_b128 v[220:223], v178 offset:25856
	s_waitcnt lgkmcnt(7)
	v_mfma_f32_16x16x32_bf16 v[50:53], v[224:227], v[26:29], v[50:53]
	ds_read_b128 v[224:227], v178 offset:26112
	s_waitcnt lgkmcnt(7)
	v_mfma_f32_16x16x32_bf16 v[26:29], v[228:231], v[26:29], v[54:57]
	ds_read_b128 v[228:231], v178 offset:26368
	s_waitcnt lgkmcnt(7)
	v_mfma_f32_16x16x32_bf16 v[22:25], v[200:203], v[10:13], v[22:25]
	ds_read_b128 v[200:203], v178 offset:32768
	s_waitcnt lgkmcnt(7)
; #define LAS __attribute__((address_space(3)))
; __device__ __forceinline__ unsigned cvt_pk_bf16(float lo, float hi) { unsigned r; asm volatile("v_cvt_pk_bf16_f32 %0, %1, %2" : "=v"(r) : "v"(lo), "v"(hi)); return r; }
; template <bool LOCAL>
; __device__ __forceinline__ void attn_unit(const bf16_t* Q, const bf16_t* KT, const bf16_t* VT, bf16_t* O, LAS unsigned char* lds, int b, int h, int r, int w, int tq, int lane) {
;     ...
;     {
;         const LAS unsigned char* vl = lds + 65536 + g * 2048 + q * 16;
; #pragma unroll
;         for (int p = 0; p < 8; ++p)
; #pragma unroll
;             for (int df = 0; df < 8; ++df) o[df] = __builtin_amdgcn_mfma_f32_16x16x32_bf16(*(const LAS bf16x8*)(vl + p * 8192 + df * 256), pb[CP + p], o[df], 0, 0, 0);
;     }
;     const float inv = 1.f / sum;
;     bf16_t* op = O + (size_t)qrow * D + h * HD + 4 * g;
; #pragma unroll
;     for (int df = 0; df < 8; ++df) { u32x2 wv; wv.x = cvt_pk_bf16(o[df][0] * inv, o[df][1] * inv); wv.y = cvt_pk_bf16(o[df][2] * inv, o[df][3] * inv); *(u32x2*)(op + 16 * df) = wv; }
	v_mfma_f32_16x16x32_bf16 v[30:33], v[204:207], v[10:13], v[30:33]
	ds_read_b128 v[204:207], v178 offset:33024
	s_waitcnt lgkmcnt(7)
	v_mfma_f32_16x16x32_bf16 v[34:37], v[208:211], v[10:13], v[34:37]
	ds_read_b128 v[208:211], v178 offset:33280
	s_waitcnt lgkmcnt(7)
	v_mfma_f32_16x16x32_bf16 v[38:41], v[212:215], v[10:13], v[38:41]
	ds_read_b128 v[212:215], v178 offset:33536
	s_waitcnt lgkmcnt(7)
	v_mfma_f32_16x16x32_bf16 v[42:45], v[216:219], v[10:13], v[42:45]
	ds_read_b128 v[216:219], v178 offset:33792
	s_waitcnt lgkmcnt(7)
	v_mfma_f32_16x16x32_bf16 v[46:49], v[220:223], v[10:13], v[46:49]
	ds_read_b128 v[220:223], v178 offset:34048
	s_waitcnt lgkmcnt(7)
	v_mfma_f32_16x16x32_bf16 v[50:53], v[224:227], v[10:13], v[50:53]
	ds_read_b128 v[224:227], v178 offset:34304
	s_waitcnt lgkmcnt(7)
	v_mfma_f32_16x16x32_bf16 v[10:13], v[228:231], v[10:13], v[26:29]
	ds_read_b128 v[228:231], v178 offset:34560
	s_waitcnt lgkmcnt(7)
	v_mfma_f32_16x16x32_bf16 v[22:25], v[200:203], v[2:5], v[22:25]
	ds_read_b128 v[200:203], v178 offset:40960
	s_waitcnt lgkmcnt(7)
	v_mfma_f32_16x16x32_bf16 v[26:29], v[204:207], v[2:5], v[30:33]
	ds_read_b128 v[204:207], v178 offset:41216
	s_waitcnt lgkmcnt(7)
	v_mfma_f32_16x16x32_bf16 v[30:33], v[208:211], v[2:5], v[34:37]
	ds_read_b128 v[208:211], v178 offset:41472
	s_waitcnt lgkmcnt(7)
	v_mfma_f32_16x16x32_bf16 v[34:37], v[212:215], v[2:5], v[38:41]
	ds_read_b128 v[212:215], v178 offset:41728
	s_waitcnt lgkmcnt(7)
	v_mfma_f32_16x16x32_bf16 v[38:41], v[216:219], v[2:5], v[42:45]
	ds_read_b128 v[216:219], v178 offset:41984
	s_waitcnt lgkmcnt(7)
	v_mfma_f32_16x16x32_bf16 v[42:45], v[220:223], v[2:5], v[46:49]
	ds_read_b128 v[220:223], v178 offset:42240
	s_waitcnt lgkmcnt(7)
	v_mfma_f32_16x16x32_bf16 v[46:49], v[224:227], v[2:5], v[50:53]
	ds_read_b128 v[224:227], v178 offset:42496
	s_waitcnt lgkmcnt(7)
	v_mfma_f32_16x16x32_bf16 v[2:5], v[228:231], v[2:5], v[10:13]
	ds_read_b128 v[228:231], v178 offset:42752
	s_waitcnt lgkmcnt(7)
	v_mfma_f32_16x16x32_bf16 v[10:13], v[200:203], v[6:9], v[22:25]
	ds_read_b128 v[200:203], v178 offset:49152
	s_waitcnt lgkmcnt(7)
	v_mfma_f32_16x16x32_bf16 v[22:25], v[204:207], v[6:9], v[26:29]
	ds_read_b128 v[204:207], v178 offset:49408
	s_waitcnt lgkmcnt(7)
	v_mfma_f32_16x16x32_bf16 v[26:29], v[208:211], v[6:9], v[30:33]
	ds_read_b128 v[208:211], v178 offset:49664
	s_waitcnt lgkmcnt(7)
	v_mfma_f32_16x16x32_bf16 v[30:33], v[212:215], v[6:9], v[34:37]
	ds_read_b128 v[212:215], v178 offset:49920
	s_waitcnt lgkmcnt(7)
	v_mfma_f32_16x16x32_bf16 v[34:37], v[216:219], v[6:9], v[38:41]
	ds_read_b128 v[216:219], v178 offset:50176
	s_waitcnt lgkmcnt(7)
	v_mfma_f32_16x16x32_bf16 v[38:41], v[220:223], v[6:9], v[42:45]
	ds_read_b128 v[220:223], v178 offset:50432
	s_waitcnt lgkmcnt(7)
	v_mfma_f32_16x16x32_bf16 v[42:45], v[224:227], v[6:9], v[46:49]
	ds_read_b128 v[224:227], v178 offset:50688
	s_waitcnt lgkmcnt(7)
	v_mfma_f32_16x16x32_bf16 v[2:5], v[228:231], v[6:9], v[2:5]
	ds_read_b128 v[228:231], v178 offset:50944
	s_waitcnt lgkmcnt(7)
	v_mfma_f32_16x16x32_bf16 v[6:9], v[200:203], v[14:17], v[10:13]
	ds_read_b128 v[200:203], v178 offset:57344
	s_waitcnt lgkmcnt(7)
	v_mfma_f32_16x16x32_bf16 v[10:13], v[204:207], v[14:17], v[22:25]
	ds_read_b128 v[204:207], v178 offset:57600
	s_waitcnt lgkmcnt(7)
	v_mfma_f32_16x16x32_bf16 v[22:25], v[208:211], v[14:17], v[26:29]
	ds_read_b128 v[208:211], v178 offset:57856
	s_waitcnt lgkmcnt(7)
	v_mfma_f32_16x16x32_bf16 v[26:29], v[212:215], v[14:17], v[30:33]
	ds_read_b128 v[212:215], v178 offset:58112
	s_waitcnt lgkmcnt(7)
	v_mfma_f32_16x16x32_bf16 v[30:33], v[216:219], v[14:17], v[34:37]
	ds_read_b128 v[216:219], v178 offset:58368
	s_waitcnt lgkmcnt(7)
	v_mfma_f32_16x16x32_bf16 v[34:37], v[220:223], v[14:17], v[38:41]
	ds_read_b128 v[220:223], v178 offset:58624
	s_waitcnt lgkmcnt(7)
	v_mfma_f32_16x16x32_bf16 v[38:41], v[224:227], v[14:17], v[42:45]
	ds_read_b128 v[224:227], v178 offset:58880
	s_waitcnt lgkmcnt(7)
	v_mfma_f32_16x16x32_bf16 v[2:5], v[228:231], v[14:17], v[2:5]
	ds_read_b128 v[228:231], v178 offset:59136
	s_waitcnt lgkmcnt(7)
	v_mfma_f32_16x16x32_bf16 v[6:9], v[200:203], v[18:21], v[6:9]
	s_waitcnt lgkmcnt(6)
	v_mfma_f32_16x16x32_bf16 v[10:13], v[204:207], v[18:21], v[10:13]
	s_waitcnt lgkmcnt(5)
	v_mfma_f32_16x16x32_bf16 v[14:17], v[208:211], v[18:21], v[22:25]
	s_waitcnt lgkmcnt(4)
	v_mfma_f32_16x16x32_bf16 v[22:25], v[212:215], v[18:21], v[26:29]
	s_waitcnt lgkmcnt(3)
	v_mfma_f32_16x16x32_bf16 v[26:29], v[216:219], v[18:21], v[30:33]
	s_waitcnt lgkmcnt(2)
	v_mfma_f32_16x16x32_bf16 v[30:33], v[220:223], v[18:21], v[34:37]
	s_waitcnt lgkmcnt(1)
	v_mfma_f32_16x16x32_bf16 v[34:37], v[224:227], v[18:21], v[38:41]
	s_waitcnt lgkmcnt(0)
	v_mfma_f32_16x16x32_bf16 v[2:5], v[228:231], v[18:21], v[2:5]
	s_nop 7
	v_add_f32_e32 v18, v134, v135
	v_div_scale_f32 v19, s[4:5], v18, v18, 1.0
	v_rcp_f32_e32 v20, v19
	s_nop 0
	v_fma_f32 v21, -v19, v20, 1.0
	v_fmac_f32_e32 v20, v21, v20
	v_div_scale_f32 v21, vcc, 1.0, v18, 1.0
	v_mul_f32_e32 v38, v21, v20
	v_fma_f32 v39, -v19, v38, v21
	v_fmac_f32_e32 v38, v39, v20
	v_fma_f32 v19, -v19, v38, v21
	v_div_fmas_f32 v19, v19, v20, v38
	v_div_fixup_f32 v20, v19, v18, 1.0
	v_mul_f32_e32 v6, v20, v6
	v_mul_f32_e32 v7, v20, v7
	v_cvt_pk_bf16_f32 v6, v6, v7
	v_mul_f32_e32 v7, v20, v8
	v_lshl_add_u64 v[18:19], v[130:131], 1, v[160:161]
	v_mul_f32_e32 v8, v20, v9
	v_cvt_pk_bf16_f32 v7, v7, v8
	global_store_dwordx2 v[18:19], v[6:7], off
	v_mul_f32_e32 v6, v20, v10
	v_mul_f32_e32 v7, v20, v11
	v_cvt_pk_bf16_f32 v6, v6, v7
	v_mul_f32_e32 v7, v20, v12
	v_mul_f32_e32 v8, v20, v13
	v_cvt_pk_bf16_f32 v7, v7, v8
	global_store_dwordx2 v[18:19], v[6:7], off offset:32
	v_mul_f32_e32 v6, v20, v14
	v_mul_f32_e32 v7, v20, v15
	v_cvt_pk_bf16_f32 v6, v6, v7
	v_mul_f32_e32 v7, v20, v16
	v_mul_f32_e32 v8, v20, v17
	v_cvt_pk_bf16_f32 v7, v7, v8
	global_store_dwordx2 v[18:19], v[6:7], off offset:64
	v_mul_f32_e32 v6, v20, v22
	v_mul_f32_e32 v7, v20, v23
	v_cvt_pk_bf16_f32 v6, v6, v7
	v_mul_f32_e32 v7, v20, v24
	v_mul_f32_e32 v8, v20, v25
	v_cvt_pk_bf16_f32 v7, v7, v8
	global_store_dwordx2 v[18:19], v[6:7], off offset:96
	v_mul_f32_e32 v6, v20, v26
	v_mul_f32_e32 v7, v20, v27
	v_cvt_pk_bf16_f32 v6, v6, v7
	v_mul_f32_e32 v7, v20, v28
	v_mul_f32_e32 v8, v20, v29
	v_cvt_pk_bf16_f32 v7, v7, v8
	global_store_dwordx2 v[18:19], v[6:7], off offset:128
	v_mul_f32_e32 v6, v20, v30
	v_mul_f32_e32 v7, v20, v31
	v_cvt_pk_bf16_f32 v6, v6, v7
	v_mul_f32_e32 v7, v20, v32
	v_mul_f32_e32 v8, v20, v33
	v_cvt_pk_bf16_f32 v7, v7, v8
	global_store_dwordx2 v[18:19], v[6:7], off offset:160
	v_mul_f32_e32 v6, v20, v34
	v_mul_f32_e32 v7, v20, v35
	v_cvt_pk_bf16_f32 v6, v6, v7
	v_mul_f32_e32 v7, v20, v36
	v_mul_f32_e32 v2, v20, v2
	v_mul_f32_e32 v3, v20, v3
	v_mul_f32_e32 v8, v20, v37
	v_cvt_pk_bf16_f32 v7, v7, v8
	global_store_dwordx2 v[18:19], v[6:7], off offset:192
	v_cvt_pk_bf16_f32 v2, v2, v3
	v_mul_f32_e32 v3, v20, v4
	v_mul_f32_e32 v4, v20, v5
	v_cvt_pk_bf16_f32 v3, v3, v4
	global_store_dwordx2 v[18:19], v[2:3], off offset:224
	s_waitcnt vmcnt(0)
	s_barrier
; template <bool LOCAL>
; __device__ __forceinline__ void attn_unit(const bf16_t* Q, const bf16_t* KT, const bf16_t* VT, bf16_t* O, LAS unsigned char* lds, int b, int h, int r, int w, int tq, int lane) {
;     ...
;     { const bf16_t* qp = Q + (size_t)qrow * D + h * HD + 8 * g;
; #pragma unroll
;       for (int ks = 0; ks < 4; ++ks) bq[ks] = *(const bf16x8*)(qp + 32 * ks); }
	s_cbranch_scc1 .LBB9_802
	v_mov_b32_e32 v138, v106
	v_mov_b32_e32 v139, v107
	v_mov_b32_e32 v140, v108
	v_mov_b32_e32 v141, v109
	v_mov_b32_e32 v134, v110
	v_mov_b32_e32 v135, v111
	v_mov_b32_e32 v136, v112
	v_mov_b32_e32 v137, v113
	v_mov_b32_e32 v130, v114
	v_mov_b32_e32 v131, v115
	v_mov_b32_e32 v132, v116
	v_mov_b32_e32 v133, v117
	v_mov_b32_e32 v62, v118
	v_mov_b32_e32 v63, v119
	v_mov_b32_e32 v64, v120
	v_mov_b32_e32 v65, v121
	s_mov_b32 s4, s52
	s_branch .Lq_loaded

; #define ATT_KLOAD(buf, p) do { const bf16_t* kp_ = kloc + (size_t)((p) * 8 * NH) * 1024; \
;         _Pragma("unroll") for (int f = 0; f < 2; ++f) _Pragma("unroll") for (int ks = 0; ks < 4; ++ks) ka[buf][f * 4 + ks] = *(const bf16x8*)(kp_ + f * 128 + ks * 256); } while (0)
; template <bool LOCAL>
; __device__ __forceinline__ void attn_unit(const bf16_t* Q, const bf16_t* KT, const bf16_t* VT, bf16_t* O, LAS unsigned char* lds, int b, int h, int r, int w, int tq, int lane) {
;     ...
;     int rs = 0, ws = 0;
;     if (LOCAL) { rs = r - 4; rs = rs < 0 ? 0 : (rs > 24 ? 24 : rs); ws = 16 * w - 8; ws = ws < 0 ? 0 : (ws > 32 ? 32 : ws); }
;     const int rgl = b * SEQ + rs * GRID_W + ws;
;     if (LOCAL) {
;         const bf16_t* kloc = KT + ((size_t)(((rgl >> 3) + (q >> 2)) * NH + h)) * 1024 + (q & 3) * 32 + g * 8;
;         bf16x8 ka[2][8];
;     ...
;         ATT_KLOAD(0, 0);
; #pragma unroll
;         for (int p = 0; p < 8; ++p) {
;             __builtin_amdgcn_s_barrier();
;             if (p + 1 < 8) ATT_KLOAD((p + 1) & 1, p + 1);
;             __builtin_amdgcn_sched_barrier(0);
; #pragma unroll
;             for (int f = 0; f < 2; ++f) { f32x4 a = {0.f, 0.f, 0.f, 0.f};
; #pragma unroll
;                 for (int ks = 0; ks < 4; ++ks) a = __builtin_amdgcn_mfma_f32_16x16x32_bf16(ka[p & 1][f * 4 + ks], bq[ks], a, 0, 0, 0);
;                 s[2 * p + f] = a; }
;             __builtin_amdgcn_sched_barrier(0);
;         }
.Lq_loaded:
	v_med3_i32 v2, s4, 4, 28
	v_lshlrev_b32_e32 v2, 6, v2
	v_add_u32_e32 v2, v2, v157
	v_add_u32_e32 v2, 0xffffff00, v2
	v_ashrrev_i32_e32 v194, 3, v2
	v_add_u32_e32 v2, v194, v168
	v_lshl_or_b32 v2, v2, 4, s72
	v_ashrrev_i32_e32 v3, 31, v2
	v_lshlrev_b64 v[2:3], 11, v[2:3]
	v_lshl_add_u64 v[70:71], v[146:147], 0, v[2:3]
	v_med3_i32 v232, s52, 4, 28
	v_add_u32_e32 v195, s51, v232
	s_lshr_b32 s54, s57, 2
	s_sub_i32 s54, s52, s54
	s_add_i32 s55, s54, -4
	s_max_i32 s55, s55, 0
	s_min_i32 s55, s55, 24
	s_add_i32 s73, s54, -3
	s_max_i32 s73, s73, 0
	s_min_i32 s73, s73, 24
	s_sub_i32 s73, s73, s55
	s_lshr_b32 s54, s57, 2
	s_mul_i32 s53, s73, s54
	s_ashr_i32 s54, s70, 6
	s_lshl_b32 s54, s54, 8
	s_lshl_b32 s55, s55, 3
	s_add_i32 s54, s54, s55
	s_add_i32 s54, s54, s57
	s_lshl_b32 s54, s54, 15
	s_lshl_b32 s55, s72, 11
	s_add_i32 s28, s54, s55
	s_mov_b32 s75, 0x200000
	s_lshl_b32 s54, s57, 10
	s_add_i32 s59, s54, 0x10000
	s_and_b32 s54, s57, 1
	s_lshl_b32 s54, s54, 1
	v_xor_b32_e32 v218, s54, v164
	v_lshlrev_b32_e32 v218, 4, v218
	v_add_u32_e32 v218, s28, v218
	ds_read_b64 v[220:221], v241 offset:192
	s_waitcnt lgkmcnt(0)
	v_add_co_u32_e32 v220, vcc, 0x21f00000, v220
	s_nop 1
	v_addc_co_u32_e32 v221, vcc, 0, v221, vcc
	v_add_co_u32_e32 v220, vcc, v220, v218
	s_nop 1
	v_addc_co_u32_e32 v221, vcc, 0, v221, vcc
	v_add_co_u32_e32 v226, vcc, 0x400, v220
	s_nop 1
	v_addc_co_u32_e32 v227, vcc, 0, v221, vcc
	s_and_b32 s55, s57, 3
	s_lshl_b32 s55, s55, 1
	s_add_i32 s55, s55, -1
	s_max_i32 s55, s55, 0
	s_min_i32 s55, s55, 4
	v_lshrrev_b32_e32 v219, 2, v166
	v_add_u32_e32 v219, s55, v219
	v_and_b32_e32 v224, 3, v166
	v_lshl_or_b32 v224, v224, 2, v165
	v_and_b32_e32 v225, 1, v219
	v_lshlrev_b32_e32 v225, 1, v225
	v_xor_b32_e32 v224, v224, v225
	v_lshlrev_b32_e32 v224, 4, v224
	v_lshl_add_u32 v219, v219, 10, v224
	v_add_u32_e32 v219, 0x10000, v219
	s_add_i32 m0, s59, 0
	s_nop 0
	global_load_lds_dwordx4 v[220:221], off
	s_add_i32 m0, s59, 8192
	s_nop 0
	global_load_lds_dwordx4 v[226:227], off
	s_add_i32 m0, s59, 16384
	v_add_co_u32_e32 v222, vcc, s6, v220
	s_nop 1
	v_addc_co_u32_e32 v223, vcc, 0, v221, vcc
	global_load_lds_dwordx4 v[222:223], off
	s_add_i32 m0, s59, 24576
	v_add_co_u32_e32 v222, vcc, s6, v226
	s_nop 1
	v_addc_co_u32_e32 v223, vcc, 0, v227, vcc
	global_load_lds_dwordx4 v[222:223], off
	s_add_i32 m0, s59, 32768
	v_add_co_u32_e32 v222, vcc, s7, v220
	s_nop 1
	v_addc_co_u32_e32 v223, vcc, 0, v221, vcc
	global_load_lds_dwordx4 v[222:223], off
	s_add_i32 m0, s59, 40960
	v_add_co_u32_e32 v222, vcc, s7, v226
	s_nop 1
	v_addc_co_u32_e32 v223, vcc, 0, v227, vcc
	global_load_lds_dwordx4 v[222:223], off
	s_add_i32 m0, s59, 49152
	v_add_co_u32_e32 v222, vcc, s2, v220
	s_nop 1
	v_addc_co_u32_e32 v223, vcc, 0, v221, vcc
	global_load_lds_dwordx4 v[222:223], off
	s_cmp_eq_u32 s53, 0
	s_cbranch_scc0 .Lrg_k_B
	s_waitcnt vmcnt(6)
	s_barrier
	ds_read_b128 v[2:5], v219 offset:0
	ds_read_b128 v[6:9], v219 offset:256
	ds_read_b128 v[10:13], v219 offset:512
	ds_read_b128 v[14:17], v219 offset:768
	s_waitcnt vmcnt(5)
	s_barrier
	s_add_i32 m0, s59, 57344
	v_add_co_u32_e32 v222, vcc, s2, v226
	s_nop 1
	v_addc_co_u32_e32 v223, vcc, 0, v227, vcc
	global_load_lds_dwordx4 v[222:223], off
	ds_read_b128 v[18:21], v219 offset:8192
	ds_read_b128 v[22:25], v219 offset:8448
	ds_read_b128 v[26:29], v219 offset:8704
	ds_read_b128 v[30:33], v219 offset:8960
	s_waitcnt lgkmcnt(4)
	v_mfma_f32_16x16x32_bf16 v[126:129], v[2:5], v[138:141], 0
	v_mfma_f32_16x16x32_bf16 v[122:125], v[6:9], v[138:141], 0
	v_mfma_f32_16x16x32_bf16 v[126:129], v[10:13], v[134:137], v[126:129]
	v_mfma_f32_16x16x32_bf16 v[122:125], v[14:17], v[134:137], v[122:125]
	s_waitcnt vmcnt(5)
	s_barrier
	s_add_i32 m0, s59, 0
	v_add_co_u32_e32 v222, vcc, s60, v220
	s_nop 1
	v_addc_co_u32_e32 v223, vcc, 0, v221, vcc
	global_load_lds_dwordx4 v[222:223], off
	ds_read_b128 v[2:5], v219 offset:16384
	ds_read_b128 v[6:9], v219 offset:16640
	ds_read_b128 v[10:13], v219 offset:16896
	ds_read_b128 v[14:17], v219 offset:17152
	s_waitcnt lgkmcnt(4)
	v_mfma_f32_16x16x32_bf16 v[126:129], v[18:21], v[130:133], v[126:129]
	v_mfma_f32_16x16x32_bf16 v[122:125], v[22:25], v[130:133], v[122:125]
	v_mfma_f32_16x16x32_bf16 v[126:129], v[26:29], v[62:65], v[126:129]
	v_mfma_f32_16x16x32_bf16 v[122:125], v[30:33], v[62:65], v[122:125]
	s_waitcnt vmcnt(5)
	s_barrier
; #define ATT_KLOAD(buf, p) do { const bf16_t* kp_ = kloc + (size_t)((p) * 8 * NH) * 1024; \
;         _Pragma("unroll") for (int f = 0; f < 2; ++f) _Pragma("unroll") for (int ks = 0; ks < 4; ++ks) ka[buf][f * 4 + ks] = *(const bf16x8*)(kp_ + f * 128 + ks * 256); } while (0)
; template <bool LOCAL>
; __device__ __forceinline__ void attn_unit(const bf16_t* Q, const bf16_t* KT, const bf16_t* VT, bf16_t* O, LAS unsigned char* lds, int b, int h, int r, int w, int tq, int lane) {
;     ...
;     if (LOCAL) {
;         const bf16_t* kloc = KT + ((size_t)(((rgl >> 3) + (q >> 2)) * NH + h)) * 1024 + (q & 3) * 32 + g * 8;
;         bf16x8 ka[2][8];
;     ...
;         ATT_KLOAD(0, 0);
; #pragma unroll
;         for (int p = 0; p < 8; ++p) {
;             __builtin_amdgcn_s_barrier();
;             if (p + 1 < 8) ATT_KLOAD((p + 1) & 1, p + 1);
;             __builtin_amdgcn_sched_barrier(0);
; #pragma unroll
;             for (int f = 0; f < 2; ++f) { f32x4 a = {0.f, 0.f, 0.f, 0.f};
; #pragma unroll
;                 for (int ks = 0; ks < 4; ++ks) a = __builtin_amdgcn_mfma_f32_16x16x32_bf16(ka[p & 1][f * 4 + ks], bq[ks], a, 0, 0, 0);
;                 s[2 * p + f] = a; }
;             __builtin_amdgcn_sched_barrier(0);
;         }
	s_add_i32 m0, s59, 8192
	v_add_co_u32_e32 v222, vcc, s60, v226
	s_nop 1
	v_addc_co_u32_e32 v223, vcc, 0, v227, vcc
	global_load_lds_dwordx4 v[222:223], off
	ds_read_b128 v[18:21], v219 offset:24576
	ds_read_b128 v[22:25], v219 offset:24832
	ds_read_b128 v[26:29], v219 offset:25088
	ds_read_b128 v[30:33], v219 offset:25344
	s_waitcnt lgkmcnt(4)
	v_mfma_f32_16x16x32_bf16 v[118:121], v[2:5], v[138:141], 0
	v_mfma_f32_16x16x32_bf16 v[114:117], v[6:9], v[138:141], 0
	v_mfma_f32_16x16x32_bf16 v[118:121], v[10:13], v[134:137], v[118:121]
	v_mfma_f32_16x16x32_bf16 v[114:117], v[14:17], v[134:137], v[114:117]
	s_waitcnt vmcnt(5)
	s_barrier
	s_add_i32 m0, s59, 16384
	v_add_co_u32_e32 v222, vcc, s61, v220
	s_nop 1
	v_addc_co_u32_e32 v223, vcc, 0, v221, vcc
	global_load_lds_dwordx4 v[222:223], off
	ds_read_b128 v[2:5], v219 offset:32768
	ds_read_b128 v[6:9], v219 offset:33024
	ds_read_b128 v[10:13], v219 offset:33280
	ds_read_b128 v[14:17], v219 offset:33536
	s_waitcnt lgkmcnt(4)
	v_mfma_f32_16x16x32_bf16 v[118:121], v[18:21], v[130:133], v[118:121]
	v_mfma_f32_16x16x32_bf16 v[114:117], v[22:25], v[130:133], v[114:117]
	v_mfma_f32_16x16x32_bf16 v[118:121], v[26:29], v[62:65], v[118:121]
	v_mfma_f32_16x16x32_bf16 v[114:117], v[30:33], v[62:65], v[114:117]
	s_waitcnt vmcnt(5)
	s_barrier
	s_add_i32 m0, s59, 24576
	v_add_co_u32_e32 v222, vcc, s61, v226
	s_nop 1
	v_addc_co_u32_e32 v223, vcc, 0, v227, vcc
	global_load_lds_dwordx4 v[222:223], off
	ds_read_b128 v[18:21], v219 offset:40960
	ds_read_b128 v[22:25], v219 offset:41216
	ds_read_b128 v[26:29], v219 offset:41472
	ds_read_b128 v[30:33], v219 offset:41728
	s_waitcnt lgkmcnt(4)
	v_mfma_f32_16x16x32_bf16 v[110:113], v[2:5], v[138:141], 0
	v_mfma_f32_16x16x32_bf16 v[106:109], v[6:9], v[138:141], 0
	v_mfma_f32_16x16x32_bf16 v[110:113], v[10:13], v[134:137], v[110:113]
	v_mfma_f32_16x16x32_bf16 v[106:109], v[14:17], v[134:137], v[106:109]
	s_waitcnt vmcnt(5)
	s_barrier
	s_add_i32 m0, s59, 32768
	v_add_co_u32_e32 v222, vcc, s17, v220
	s_nop 1
	v_addc_co_u32_e32 v223, vcc, 0, v221, vcc
	global_load_lds_dwordx4 v[222:223], off
	ds_read_b128 v[2:5], v219 offset:49152
	ds_read_b128 v[6:9], v219 offset:49408
	ds_read_b128 v[10:13], v219 offset:49664
	ds_read_b128 v[14:17], v219 offset:49920
	s_waitcnt lgkmcnt(4)
	v_mfma_f32_16x16x32_bf16 v[110:113], v[18:21], v[130:133], v[110:113]
	v_mfma_f32_16x16x32_bf16 v[106:109], v[22:25], v[130:133], v[106:109]
	v_mfma_f32_16x16x32_bf16 v[110:113], v[26:29], v[62:65], v[110:113]
	v_mfma_f32_16x16x32_bf16 v[106:109], v[30:33], v[62:65], v[106:109]
	s_waitcnt vmcnt(5)
	s_barrier
	s_add_i32 m0, s59, 40960
	v_add_co_u32_e32 v222, vcc, s17, v226
	s_nop 1
	v_addc_co_u32_e32 v223, vcc, 0, v227, vcc
	global_load_lds_dwordx4 v[222:223], off
	ds_read_b128 v[18:21], v219 offset:57344
	ds_read_b128 v[22:25], v219 offset:57600
	ds_read_b128 v[26:29], v219 offset:57856
	ds_read_b128 v[30:33], v219 offset:58112
	s_waitcnt lgkmcnt(4)
	v_mfma_f32_16x16x32_bf16 v[102:105], v[2:5], v[138:141], 0
	v_mfma_f32_16x16x32_bf16 v[98:101], v[6:9], v[138:141], 0
	v_mfma_f32_16x16x32_bf16 v[102:105], v[10:13], v[134:137], v[102:105]
	v_mfma_f32_16x16x32_bf16 v[98:101], v[14:17], v[134:137], v[98:101]
	s_waitcnt vmcnt(5)
	s_barrier
	s_add_i32 m0, s59, 49152
	v_add_co_u32_e32 v222, vcc, s62, v220
	s_nop 1
	v_addc_co_u32_e32 v223, vcc, 0, v221, vcc
	global_load_lds_dwordx4 v[222:223], off
	ds_read_b128 v[2:5], v219 offset:0
	ds_read_b128 v[6:9], v219 offset:256
	ds_read_b128 v[10:13], v219 offset:512
	ds_read_b128 v[14:17], v219 offset:768
	s_waitcnt lgkmcnt(4)
	v_mfma_f32_16x16x32_bf16 v[102:105], v[18:21], v[130:133], v[102:105]
	v_mfma_f32_16x16x32_bf16 v[98:101], v[22:25], v[130:133], v[98:101]
	v_mfma_f32_16x16x32_bf16 v[102:105], v[26:29], v[62:65], v[102:105]
	v_mfma_f32_16x16x32_bf16 v[98:101], v[30:33], v[62:65], v[98:101]
	s_waitcnt vmcnt(5)
	s_barrier
	s_add_i32 m0, s59, 57344
	v_add_co_u32_e32 v222, vcc, s62, v226
	s_nop 1
	v_addc_co_u32_e32 v223, vcc, 0, v227, vcc
	global_load_lds_dwordx4 v[222:223], off
	ds_read_b128 v[18:21], v219 offset:8192
	ds_read_b128 v[22:25], v219 offset:8448
	ds_read_b128 v[26:29], v219 offset:8704
	ds_read_b128 v[30:33], v219 offset:8960
	s_waitcnt lgkmcnt(4)
	v_mfma_f32_16x16x32_bf16 v[94:97], v[2:5], v[138:141], 0
	v_mfma_f32_16x16x32_bf16 v[90:93], v[6:9], v[138:141], 0
	v_mfma_f32_16x16x32_bf16 v[94:97], v[10:13], v[134:137], v[94:97]
	v_mfma_f32_16x16x32_bf16 v[90:93], v[14:17], v[134:137], v[90:93]
	s_waitcnt vmcnt(5)
	s_barrier
	s_cmp_eq_u32 s73, 0
	s_cbranch_scc1 .Lrg_k_A_nd9
	s_add_i32 m0, s59, 0
	v_add_co_u32_e32 v222, vcc, s75, v220
	s_nop 1
	v_addc_co_u32_e32 v223, vcc, 0, v221, vcc
	global_load_lds_dwordx4 v[222:223], off
